# v88 plus sample-mLSTM q.C0 pass: the 32 cold state-row loads of each loop trip issued together (were one or two at a time with a wait each)
# speedup vs baseline: 1.0066x; 1.0066x over previous
.LBB0_1001:
	v_lshl_add_u64 v[10:11], v[6:7], 0, s[10:11]
	v_mov_b32_e32 v216, 0x2000
	v_mov_b32_e32 v217, 0
	v_lshl_add_u64 v[212:213], v[10:11], 0, v[216:217]
	v_mov_b32_e32 v216, 0x4000
	v_lshl_add_u64 v[214:215], v[10:11], 0, v[216:217]
	global_load_dword v180, v[10:11], off
	global_load_dword v181, v[10:11], off offset:512
	global_load_dword v182, v[10:11], off offset:1024
	global_load_dword v183, v[10:11], off offset:1536
	global_load_dword v184, v[10:11], off offset:2048
	global_load_dword v185, v[10:11], off offset:2560
	global_load_dword v186, v[10:11], off offset:3072
	global_load_dword v187, v[10:11], off offset:3584
	global_load_dword v188, v[212:213], off offset:-4096
	global_load_dword v189, v[212:213], off offset:-3584
	global_load_dword v190, v[212:213], off offset:-3072
	global_load_dword v191, v[212:213], off offset:-2560
	global_load_dword v192, v[212:213], off offset:-2048
	global_load_dword v193, v[212:213], off offset:-1536
	global_load_dword v194, v[212:213], off offset:-1024
	global_load_dword v195, v[212:213], off offset:-512
	global_load_dword v196, v[212:213], off
	global_load_dword v197, v[212:213], off offset:512
	global_load_dword v198, v[212:213], off offset:1024
	global_load_dword v199, v[212:213], off offset:1536
	global_load_dword v200, v[212:213], off offset:2048
	global_load_dword v201, v[212:213], off offset:2560
	global_load_dword v202, v[212:213], off offset:3072
	global_load_dword v203, v[212:213], off offset:3584
	global_load_dword v204, v[214:215], off offset:-4096
	global_load_dword v205, v[214:215], off offset:-3584
	global_load_dword v206, v[214:215], off offset:-3072
	global_load_dword v207, v[214:215], off offset:-2560
	global_load_dword v208, v[214:215], off offset:-2048
	global_load_dword v209, v[214:215], off offset:-1536
	global_load_dword v210, v[214:215], off offset:-1024
	global_load_dword v211, v[214:215], off offset:-512
	s_waitcnt vmcnt(0)
	v_mov_b32_e32 v32, v180
	ds_read_b128 v[20:23], v18
	ds_read_b128 v[24:27], v18 offset:16
	ds_read_b128 v[28:31], v18 offset:32
	ds_read_b128 v[2:5], v18 offset:48
	ds_read_b128 v[40:43], v18 offset:1024
	s_waitcnt lgkmcnt(4)
	v_mov_b32_e32 v44, v20
	v_mov_b32_e32 v20, v181
	s_add_u32 s10, s10, 0x4000
	s_addc_u32 s11, s11, 0
	s_waitcnt lgkmcnt(0)
	v_mov_b32_e32 v45, v40
	v_mov_b32_e32 v40, v21
	s_cmpk_eq_u32 s10, 0x8000
	s_nop 0
	v_pk_fma_f32 v[8:9], v[32:33], v[44:45], v[8:9] op_sel_hi:[0,1,1]
	v_mov_b32_e32 v32, v22
	v_mov_b32_e32 v33, v42
	s_nop 0
	v_pk_fma_f32 v[8:9], v[20:21], v[40:41], v[8:9] op_sel_hi:[0,1,1]
	v_mov_b32_e32 v20, v182
	v_mov_b32_e32 v40, v24
	v_mov_b32_e32 v24, v185
	v_mov_b32_e32 v42, v23
	s_nop 0
	v_pk_fma_f32 v[8:9], v[20:21], v[32:33], v[8:9] op_sel_hi:[0,1,1]
	v_mov_b32_e32 v20, v183
	v_mov_b32_e32 v32, v184
	s_nop 0
	v_pk_fma_f32 v[8:9], v[20:21], v[42:43], v[8:9] op_sel_hi:[0,1,1]
	ds_read_b128 v[20:23], v18 offset:1040
	s_waitcnt lgkmcnt(0)
	v_mov_b32_e32 v41, v20
	s_nop 0
	v_pk_fma_f32 v[8:9], v[32:33], v[40:41], v[8:9] op_sel_hi:[0,1,1]
	v_mov_b32_e32 v20, v25
	v_pk_fma_f32 v[8:9], v[24:25], v[20:21], v[8:9] op_sel_hi:[0,1,1]
	v_mov_b32_e32 v20, v186
	v_mov_b32_e32 v24, v26
	v_mov_b32_e32 v25, v22
	v_add_co_u32_e32 v26, vcc, s82, v10
	v_mov_b32_e32 v22, v27
	s_nop 0
	v_addc_co_u32_e32 v27, vcc, 0, v11, vcc
	v_mov_b32_e32 v40, v28
	v_mov_b32_e32 v28, v189
	s_nop 0
	v_pk_fma_f32 v[8:9], v[20:21], v[24:25], v[8:9] op_sel_hi:[0,1,1]
	v_mov_b32_e32 v20, v187
	s_nop 0
	v_pk_fma_f32 v[24:25], v[20:21], v[22:23], v[8:9] op_sel_hi:[0,1,1]
	v_add_co_u32_e32 v8, vcc, s67, v10
	ds_read_b128 v[20:23], v18 offset:1056
	s_nop 0
	v_addc_co_u32_e32 v9, vcc, 0, v11, vcc
	v_mov_b32_e32 v32, v188
	s_waitcnt lgkmcnt(0)
	v_mov_b32_e32 v41, v20
	v_mov_b32_e32 v20, v29
	s_nop 0
	v_pk_fma_f32 v[24:25], v[32:33], v[40:41], v[24:25] op_sel_hi:[0,1,1]
	v_pk_fma_f32 v[20:21], v[28:29], v[20:21], v[24:25] op_sel_hi:[0,1,1]
	v_mov_b32_e32 v24, v190
	v_mov_b32_e32 v28, v30
	v_mov_b32_e32 v29, v22
	v_mov_b32_e32 v30, v2
	v_mov_b32_e32 v2, v193
	v_mov_b32_e32 v22, v31
	s_nop 0
	v_pk_fma_f32 v[20:21], v[24:25], v[28:29], v[20:21] op_sel_hi:[0,1,1]
	v_mov_b32_e32 v24, v191
	v_mov_b32_e32 v28, v192
	s_nop 0
	v_pk_fma_f32 v[24:25], v[24:25], v[22:23], v[20:21] op_sel_hi:[0,1,1]
	ds_read_b128 v[20:23], v18 offset:1072
	s_waitcnt lgkmcnt(0)
	v_mov_b32_e32 v31, v20
	s_nop 0
	v_pk_fma_f32 v[24:25], v[28:29], v[30:31], v[24:25] op_sel_hi:[0,1,1]
	v_mov_b32_e32 v20, v3
	v_pk_fma_f32 v[2:3], v[2:3], v[20:21], v[24:25] op_sel_hi:[0,1,1]
	v_mov_b32_e32 v20, v194
	v_mov_b32_e32 v24, v4
	v_mov_b32_e32 v4, v195
	v_mov_b32_e32 v25, v22
	v_mov_b32_e32 v22, v5
	v_mov_b32_e32 v26, v196
	s_nop 0
	v_pk_fma_f32 v[2:3], v[20:21], v[24:25], v[2:3] op_sel_hi:[0,1,1]
	s_nop 0
	v_pk_fma_f32 v[24:25], v[4:5], v[22:23], v[2:3] op_sel_hi:[0,1,1]
	ds_read_b128 v[2:5], v18 offset:64
	ds_read_b128 v[20:23], v18 offset:1088
	s_waitcnt lgkmcnt(1)
	v_mov_b32_e32 v28, v2
	v_mov_b32_e32 v2, v197
	s_waitcnt lgkmcnt(0)
	v_mov_b32_e32 v29, v20
	s_nop 0
	v_pk_fma_f32 v[24:25], v[26:27], v[28:29], v[24:25] op_sel_hi:[0,1,1]
	v_mov_b32_e32 v20, v3
	v_mov_b32_e32 v26, v200
	s_nop 0
	v_pk_fma_f32 v[2:3], v[2:3], v[20:21], v[24:25] op_sel_hi:[0,1,1]
	v_mov_b32_e32 v20, v198
	v_mov_b32_e32 v24, v4
	v_mov_b32_e32 v4, v199
	v_mov_b32_e32 v25, v22
	v_mov_b32_e32 v22, v5
	s_nop 0
	v_pk_fma_f32 v[2:3], v[20:21], v[24:25], v[2:3] op_sel_hi:[0,1,1]
	s_nop 0
	v_pk_fma_f32 v[24:25], v[4:5], v[22:23], v[2:3] op_sel_hi:[0,1,1]
	ds_read_b128 v[2:5], v18 offset:80
	ds_read_b128 v[20:23], v18 offset:1104
	s_waitcnt lgkmcnt(1)
	v_mov_b32_e32 v28, v2
	v_mov_b32_e32 v2, v201
	s_waitcnt lgkmcnt(0)
	v_mov_b32_e32 v29, v20
	v_pk_fma_f32 v[24:25], v[26:27], v[28:29], v[24:25] op_sel_hi:[0,1,1]
	v_mov_b32_e32 v20, v3
	s_nop 0
	v_pk_fma_f32 v[2:3], v[2:3], v[20:21], v[24:25] op_sel_hi:[0,1,1]
	v_mov_b32_e32 v20, v202
	v_mov_b32_e32 v24, v4
	v_mov_b32_e32 v4, v203
	v_mov_b32_e32 v25, v22
	v_mov_b32_e32 v22, v5
	s_nop 0
	v_pk_fma_f32 v[2:3], v[20:21], v[24:25], v[2:3] op_sel_hi:[0,1,1]
	s_nop 0
	v_pk_fma_f32 v[20:21], v[4:5], v[22:23], v[2:3] op_sel_hi:[0,1,1]
	v_add_co_u32_e32 v22, vcc, s83, v10
	s_nop 1
	v_addc_co_u32_e32 v23, vcc, 0, v11, vcc
	v_mov_b32_e32 v24, v204
	ds_read_b128 v[2:5], v18 offset:96
	ds_read_b128 v[8:11], v18 offset:1120
	s_waitcnt lgkmcnt(1)
	v_mov_b32_e32 v26, v2
	v_mov_b32_e32 v2, v205
	s_waitcnt lgkmcnt(0)
	v_mov_b32_e32 v27, v8
	v_mov_b32_e32 v8, v3
	s_nop 0
	v_pk_fma_f32 v[20:21], v[24:25], v[26:27], v[20:21] op_sel_hi:[0,1,1]
	v_mov_b32_e32 v24, v208
	s_nop 0
	v_pk_fma_f32 v[2:3], v[2:3], v[8:9], v[20:21] op_sel_hi:[0,1,1]
	v_mov_b32_e32 v8, v206
	v_mov_b32_e32 v20, v4
	v_mov_b32_e32 v4, v207
	v_mov_b32_e32 v21, v10
	v_mov_b32_e32 v10, v5
	s_nop 0
	v_pk_fma_f32 v[2:3], v[8:9], v[20:21], v[2:3] op_sel_hi:[0,1,1]
	s_nop 0
	v_pk_fma_f32 v[20:21], v[4:5], v[10:11], v[2:3] op_sel_hi:[0,1,1]
	ds_read_b128 v[2:5], v18 offset:112
	ds_read_b128 v[8:11], v18 offset:1136
	v_add_u32_e32 v18, 0x80, v18
	s_waitcnt lgkmcnt(1)
	v_mov_b32_e32 v26, v2
	v_mov_b32_e32 v2, v209
	s_waitcnt lgkmcnt(0)
	v_mov_b32_e32 v27, v8
	v_pk_fma_f32 v[20:21], v[24:25], v[26:27], v[20:21] op_sel_hi:[0,1,1]
	v_mov_b32_e32 v8, v3
	s_nop 0
	v_pk_fma_f32 v[2:3], v[2:3], v[8:9], v[20:21] op_sel_hi:[0,1,1]
	v_mov_b32_e32 v8, v210
	v_mov_b32_e32 v20, v4
	v_mov_b32_e32 v4, v211
	v_mov_b32_e32 v21, v10
	v_mov_b32_e32 v10, v5
	s_nop 0
	v_pk_fma_f32 v[2:3], v[8:9], v[20:21], v[2:3] op_sel_hi:[0,1,1]
	s_nop 0
	v_pk_fma_f32 v[8:9], v[4:5], v[10:11], v[2:3] op_sel_hi:[0,1,1]
	s_cbranch_scc0 .LBB0_1001
	v_lshl_add_u32 v5, v13, 2, 0
	v_lshl_add_u32 v4, v12, 2, 0
	v_mad_u64_u32 v[10:11], s[10:11], v12, 28, v[4:5]
	s_movk_i32 s10, 0xffe4
	v_add_u32_e32 v13, 4, v12
	v_mad_u64_u32 v[2:3], s[10:11], v12, s10, v[10:11]
	v_add_u32_e32 v11, 0x2000, v4
	ds_read2st64_b32 v[46:47], v5 offset0:16 offset1:18
	ds_read2st64_b32 v[44:45], v5 offset0:20 offset1:22
	ds_read2st64_b32 v[42:43], v5 offset0:24 offset1:26
	ds_read2st64_b32 v[40:41], v5 offset0:28 offset1:30
	ds_read_b128 v[4:7], v10 offset:8192
	ds_read2_b32 v[30:31], v11 offset0:88 offset1:92
	v_lshl_add_u32 v11, v13, 5, 0
	ds_read_b128 v[18:21], v11 offset:8192
	ds_read_b128 v[22:25], v10 offset:8208
	ds_read_b128 v[26:29], v11 offset:8208
	s_waitcnt lgkmcnt(4)
	v_mul_f32_e32 v10, v46, v4
	s_waitcnt lgkmcnt(3)
	v_fmac_f32_e32 v10, v8, v30
	s_waitcnt lgkmcnt(2)
	v_mul_f32_e32 v8, v46, v18
	v_fmac_f32_e32 v8, v9, v31
	v_fmac_f32_e32 v10, v47, v5
	v_fmac_f32_e32 v8, v47, v19
	v_fmac_f32_e32 v10, v44, v6
	v_fmac_f32_e32 v8, v44, v20
	v_add_u32_e32 v4, 0x2000, v2
	v_fmac_f32_e32 v10, v45, v7
	v_fmac_f32_e32 v8, v45, v21
	ds_read2_b32 v[4:5], v4 offset0:104 offset1:108
	s_waitcnt lgkmcnt(2)
	v_fmac_f32_e32 v10, v42, v22
	s_waitcnt lgkmcnt(1)
	v_fmac_f32_e32 v8, v42, v26
	v_fmac_f32_e32 v10, v43, v23
	v_fmac_f32_e32 v8, v43, v27
	v_fmac_f32_e32 v10, v40, v24
	v_fmac_f32_e32 v8, v40, v28
	v_fmac_f32_e32 v10, v41, v25
	v_fmac_f32_e32 v8, v41, v29
	s_waitcnt lgkmcnt(0)
	v_mul_f32_e32 v58, v10, v4
	v_mul_f32_e32 v57, v8, v5
	v_mul_f32_e32 v4, v58, v58
	v_mul_f32_e32 v5, v57, v57
	ds_bpermute_b32 v4, v17, v4
	ds_bpermute_b32 v5, v17, v5
	v_xor_b32_e32 v3, 8, v249
	v_cmp_lt_i32_e32 vcc, v3, v14
	v_xor_b32_e32 v8, 16, v249
	s_waitcnt lgkmcnt(1)
	v_fmac_f32_e32 v4, v58, v58
	s_waitcnt lgkmcnt(0)
	v_fmac_f32_e32 v5, v57, v57
	ds_bpermute_b32 v6, v16, v4
	ds_bpermute_b32 v7, v16, v5
	v_cndmask_b32_e32 v3, v249, v3, vcc
	v_lshlrev_b32_e32 v3, 2, v3
	v_cmp_lt_i32_e32 vcc, v8, v14
	s_waitcnt lgkmcnt(1)
	v_add_f32_e32 v4, v4, v6
	s_waitcnt lgkmcnt(0)
	v_add_f32_e32 v5, v5, v7
	ds_bpermute_b32 v6, v15, v4
	ds_bpermute_b32 v7, v15, v5
	v_cndmask_b32_e32 v8, v249, v8, vcc
	v_lshlrev_b32_e32 v60, 3, v12
	v_lshlrev_b32_e32 v59, 3, v13
	s_waitcnt lgkmcnt(1)
	v_add_f32_e32 v4, v4, v6
	s_waitcnt lgkmcnt(0)
	v_add_f32_e32 v5, v5, v7
	ds_bpermute_b32 v6, v3, v4
	ds_bpermute_b32 v3, v3, v5
	v_lshlrev_b32_e32 v7, 2, v8
	v_xor_b32_e32 v8, 32, v249
	v_cmp_lt_i32_e32 vcc, v8, v14
	s_waitcnt lgkmcnt(1)
	v_add_f32_e32 v4, v4, v6
	s_waitcnt lgkmcnt(0)
	v_add_f32_e32 v5, v5, v3
	ds_bpermute_b32 v6, v7, v4
	ds_bpermute_b32 v7, v7, v5
	v_cndmask_b32_e32 v3, v249, v8, vcc
	v_lshlrev_b32_e32 v8, 2, v3
	v_cmp_eq_u32_e32 vcc, 0, v1
	s_waitcnt lgkmcnt(1)
	v_add_f32_e32 v3, v4, v6
	s_waitcnt lgkmcnt(0)
	v_add_f32_e32 v5, v5, v7
	ds_bpermute_b32 v4, v8, v3
	ds_bpermute_b32 v6, v8, v5
	s_and_saveexec_b64 s[10:11], vcc
	s_cbranch_execz .LBB0_1004
	v_readlane_b32 s21, v253, 23
	s_waitcnt lgkmcnt(1)
	v_add_f32_e32 v3, v3, v4
	s_waitcnt lgkmcnt(0)
	v_add_f32_e32 v5, v5, v6
	v_add_u32_e32 v4, s21, v60
	ds_write_b32 v4, v3 offset:8640
	v_add_u32_e32 v3, s21, v59
	ds_write_b32 v3, v5 offset:8640
